# mixer phase: three sub-phase orders by (blockIdx>>3)%3 instead of two
# baseline (speedup 1.0000x reference)
; #define LAS __attribute__((address_space(3)))
; #define LAUNDER() int tp = TID0(); const int tid = tp, lane = tp & 63, wave = __builtin_amdgcn_readfirstlane(tp >> 6); (void)tid; (void)lane; (void)wave
; __global__ void __launch_bounds__(512) fwd_kernel(Args a) {
;     ...
;         if (IN(pb + 2)) {
;             if (EN_B) { LAUNDER(); LAS char* vt = (LAS char*)lds + wave * 16384;
;                 (void)vt; for (int u = blockIdx.x; u < 256; u += G) { mixerB2_unit(u, l, PROJ, YC, a.in[6] + l * 128, a.in[7] + l * 64, KMAX + l * 1024, (LAS char*)lds, tid, wave, lane); } __syncthreads(); }
;             if (EN_S1) { LAUNDER(); __syncthreads();
;                 for (int u = blockIdx.x; u < 256; u += G) ssd_part1_unit(u, PROJ, DT, H, WDT + l * 16384, a.in[11] + l * 8, a.in[8] + l * 5 * 768, a.in[9] + l * 768, a.in[10] + l * 8, STATES, TOT, lds, tid, wave, lane);
;                 __syncthreads(); }
;             if (EN_A) { LAUNDER(); LAS char* vt = (LAS char*)lds + wave * 16384;
;                 for (int u = blockIdx.x; u < 512; u += G) { mixerA1_unit(u, PROJ, YC, LPA, KMAX + l * 1024, vt, wave, lane); } }
;             if (EN_D) { LAUNDER(); LAS char* vt = (LAS char*)lds + wave * 16384;
;                 int hcur = -1; float rmax = 0.f;
;                 for (int u = blockIdx.x; u < 512; u += G) { const int hd = (u >> 4) & 3; if (hd != hcur) { rmax = d_stage_rpb(a.in[14] + l * 4 * 15 * 31, hd, vt, lane); hcur = hd; }
;                     mixerD2_unit(u, PROJ, YC, rmax, KMAX + l * 1024, vt, wave, lane); } }
;         }
.Lmx_b:
	s_cmp_eq_u32 s101, 0
	s_cbranch_scc0 .Lmx_b_go
	s_lshr_b32 s98, s66, 3
	s_mul_i32 s99, s98, 0xaaab
	s_lshr_b32 s99, s99, 17
	s_mul_i32 s99, s99, 3
	s_sub_i32 s98, s98, s99
	s_cmp_eq_u32 s98, 0
	s_cbranch_scc1 .Lmx_b_go
	s_cmp_eq_u32 s98, 1
	s_cbranch_scc1 .Lmx_o2
	s_mov_b32 s101, 3
	v_readlane_b32 s56, v255, 10
	s_branch .LBB0_356
.Lmx_o2:
	s_mov_b32 s101, 1
	v_readlane_b32 s0, v253, 56
	v_readlane_b32 s1, v253, 57
	s_nop 1
	v_cndmask_b32_e64 v6, 0, 1, s[0:1]
	s_nop 0
	v_cmp_ne_u32_e64 s[36:37], 1, v6
	s_branch .LBB0_262

; #define LAS __attribute__((address_space(3)))
; #define LAUNDER() int tp = TID0(); const int tid = tp, lane = tp & 63, wave = __builtin_amdgcn_readfirstlane(tp >> 6); (void)tid; (void)lane; (void)wave
; DI void ssd_part1_unit(int u, const bf16* PROJ, float* DT, const bf16* H, const bf16* wdtb_l, const float* dt_bias_l, const float* cw, const float* cb, const float* a_log_l, float* STATES, float* TOT,
;                        LAS unsigned char* ldsu, int tid, int wave, int lane) {
;     const int b = u >> 5, c = (u >> 1) & 15, grp = u & 1, t0 = c * 128;
;     LAS char* lds = (LAS char*)ldsu;
;     LAS char* XS = lds; LAS char* BM = lds + IMG_BYTES;
;     LAS float* gtab = (LAS float*)(lds + 3 * IMG_BYTES); LAS float* wtab = gtab + 512;
;     const int r = lane & 15, g = lane >> 4, q = (lane & 15) >> 2, p = lane & 3;
;     __syncthreads();
;     {
;         LAS char* wl = lds + 3 * IMG_BYTES + 4096;
;         LAS char* hst = lds + 2 * IMG_BYTES + wave * (16 * IMG_PITCH);
;         for (int i = tid; i < 1024; i += 512) { const int row = i >> 7, ch = i & 127; *(LAS u32x4*)(wl + row * 2064 + ch * 16) = *(const u32x4*)(wdtb_l + (size_t)row * 1024 + ch * 8); }
; __global__ void __launch_bounds__(512) fwd_kernel(Args a) {
;     ...
;             if (EN_S1) { LAUNDER(); __syncthreads();
;                 for (int u = blockIdx.x; u < 256; u += G) ssd_part1_unit(u, PROJ, DT, H, WDT + l * 16384, a.in[11] + l * 8, a.in[8] + l * 5 * 768, a.in[9] + l * 768, a.in[10] + l * 8, STATES, TOT, lds, tid, wave, lane);
;                 __syncthreads(); }
.Lmx_s1_go:
	s_cmp_eq_u32 s101, 4
	s_cselect_b32 s101, 5, s101
	v_readlane_b32 s0, v253, 0
	s_waitcnt vmcnt(0)
	s_barrier
	v_mbcnt_lo_u32_b32 v4, -1, 0
	v_mbcnt_hi_u32_b32 v4, -1, v4
	s_and_b64 vcc, exec, s[36:37]
	v_add_u32_e32 v103, s0, v4
	v_readlane_b32 s56, v255, 10
	v_readfirstlane_b32 s0, v103
	s_barrier
	s_cbranch_vccnz .LBB0_356
	v_readlane_b32 s30, v255, 27
	s_lshl_b32 s34, s30, 3
	v_readlane_b32 s44, v253, 5
	s_ashr_i32 s1, s0, 6
	s_lshl_b64 s[4:5], s[34:35], 2
	v_readlane_b32 s50, v253, 11
	v_readlane_b32 s51, v253, 12
	s_add_u32 s40, s50, s4
	s_mul_i32 s34, s30, 0xf00
	s_addc_u32 s41, s51, s5
	s_lshl_b64 s[20:21], s[34:35], 2
	v_readlane_b32 s45, v253, 6
	s_add_u32 s20, s44, s20
	s_mul_i32 s34, s30, 0x300
	v_readlane_b32 s46, v253, 7
	s_addc_u32 s21, s45, s21
	s_lshl_b64 s[26:27], s[34:35], 2
	v_readlane_b32 s47, v253, 8
	s_add_u32 s26, s46, s26
	v_readlane_b32 s48, v253, 9
	s_addc_u32 s27, s47, s27
	v_readlane_b32 s49, v253, 10
	s_add_u32 s2, s48, s4
	s_addc_u32 s4, s49, s5
	s_mul_i32 s5, s1, 0x1100
	s_add_i32 s5, s5, 0
	s_movk_i32 s16, 0x400
	s_add_i32 s5, s5, 0x11000
	v_cmp_gt_i32_e64 s[36:37], s16, v103
	s_lshl_b32 s16, s30, 15
	v_readlane_b32 s30, v253, 46
	v_readlane_b32 s31, v255, 28
	s_add_u32 s30, s30, s16
	v_readlane_b32 s16, v253, 47
	v_lshlrev_b32_e32 v6, 4, v103
	s_addc_u32 s31, s16, 0
	v_and_b32_e32 v188, 0x7f0, v6
	v_readlane_b32 s16, v255, 13
	v_lshlrev_b32_e32 v8, 4, v4
	v_lshl_add_u64 v[100:101], s[30:31], 0, v[188:189]
	v_add_u32_e32 v102, s16, v188
	v_and_b32_e32 v188, 0xf0, v8
	v_and_b32_e32 v7, 15, v4
	s_lshl_b32 s30, s1, 4
	v_readlane_b32 s38, v254, 52
	v_add_u32_e32 v13, s5, v188
	v_mov_b32_e32 v14, s5
	s_movk_i32 s5, 0x110
	v_readlane_b32 s39, v254, 53
	v_mad_u32_u24 v15, v7, s5, v14
	v_mov_b32_e32 v14, s16
	v_readlane_b32 s5, v255, 14
	s_cmp_lt_i32 s1, 4
	v_lshl_add_u64 v[104:105], s[38:39], 0, v[188:189]
	v_mad_u32_u24 v19, v7, s93, v14
	v_lshlrev_b32_e32 v188, 2, v7
	v_mov_b32_e32 v14, s5
	s_movk_i32 s5, 0x100
	s_cselect_b64 s[96:97], -1, 0
	s_and_b32 s16, s1, 1
	v_lshl_add_u64 v[106:107], s[40:41], 0, v[188:189]
	v_readlane_b32 s42, v253, 44
	v_cmp_gt_u32_e64 s[40:41], s5, v103
	s_ashr_i32 s5, s0, 7
	s_lshl_b32 s33, s16, 2
	s_lshl_b32 s0, s16, 4
	v_and_b32_e32 v5, 63, v4
	v_readlane_b32 s43, v253, 45
	s_add_u32 s94, s42, s0
	v_readlane_b32 s52, v253, 13
	v_readlane_b32 s53, v253, 14
	v_lshlrev_b32_e32 v11, 3, v5
	s_addc_u32 s95, s43, 0
	v_readlane_b32 s54, v253, 15
	v_readlane_b32 s55, v253, 16
	v_lshl_add_u64 v[108:109], s[42:43], 0, v[188:189]
	v_lshlrev_b32_e32 v110, 1, v5
	v_cmp_eq_u32_e64 s[42:43], 0, v5
	v_cmp_gt_u32_e64 s[44:45], 2, v5
	v_cmp_gt_u32_e64 s[46:47], 4, v5
	v_cmp_gt_u32_e64 s[48:49], 8, v5
	v_cmp_gt_u32_e64 s[50:51], 16, v5
	v_cmp_gt_u32_e64 s[52:53], 32, v5
	s_cmp_eq_u32 s16, 0
	v_lshl_or_b32 v5, s1, 9, v11
	v_readlane_b32 s0, v255, 15
	s_cselect_b64 s[54:55], -1, 0
	s_lshl_b32 s1, s1, 5
	v_add_u32_e32 v229, s0, v5
	s_add_i32 s0, 0, 0x1a000
	v_bfe_u32 v9, v4, 4, 2
	v_lshlrev_b32_e32 v6, 6, v4
	v_and_b32_e32 v17, 48, v4
	v_add_u32_e32 v230, s0, v5
	v_bfe_u32 v4, v4, 2, 2
	s_add_i32 s1, s1, 0
	v_and_b32_e32 v5, 24, v11
	s_ashr_i32 s31, s30, 31
	v_cndmask_b32_e64 v16, v14, 0, s[40:41]
	v_lshrrev_b32_e32 v14, 1, v103
	v_add_u32_e32 v11, s1, v5
	v_lshl_or_b32 v4, v9, 3, v4
	v_lshl_add_u32 v231, v9, 5, s0
	s_lshl_b64 s[0:1], s[30:31], 2
	v_readlane_b32 s58, v253, 19
	v_readlane_b32 s59, v253, 20
	v_and_b32_e32 v6, 0xc00, v6
	v_lshlrev_b32_e32 v191, 3, v7
	v_and_b32_e32 v225, 0x78, v14
	v_mul_u32_u24_e32 v25, 0x110, v4
	v_lshlrev_b32_e32 v4, 9, v9
	s_add_u32 s0, s12, s0
	v_readlane_b32 s56, v253, 17
	v_readlane_b32 s58, v253, 24
	v_or_b32_e32 v8, 0x1000, v6
	v_or_b32_e32 v10, 0x2000, v6
	v_or_b32_e32 v12, 0x3000, v6
	v_cmp_gt_u32_e64 s[38:39], 8, v7
	v_mul_u32_u24_e32 v21, 0x110, v9
	v_and_b32_e32 v14, 56, v191
	v_lshl_add_u32 v7, v7, 4, v16
	v_mul_u32_u24_e32 v23, 0x110, v225
	s_addc_u32 s1, s13, s1
	v_or_b32_e32 v16, 0x1800, v4
	v_or_b32_e32 v18, 0x800, v4
	v_or_b32_e32 v20, 0x880, v4
	v_or_b32_e32 v22, 0x900, v4
	v_or_b32_e32 v24, 0x980, v4
	v_or_b32_e32 v26, 0x1000, v4
	v_or_b32_e32 v28, 0x1080, v4
	v_or_b32_e32 v30, 0x1100, v4
	v_or_b32_e32 v32, 0x1180, v4
	v_or_b32_e32 v34, 0x1880, v4
	v_or_b32_e32 v36, 0x1900, v4
	v_or_b32_e32 v38, 0x1980, v4
	v_readlane_b32 s59, v253, 25
	v_readlane_b32 s56, v255, 10
	v_lshlrev_b32_e32 v111, 2, v9
	v_add_u32_e32 v228, -2, v225
	v_lshl_add_u64 v[112:113], s[0:1], 0, v[188:189]
	v_add3_u32 v232, 0, v5, v25
	v_lshlrev_b32_e32 v114, 1, v6
	v_lshlrev_b32_e32 v188, 1, v8
	v_lshlrev_b32_e32 v116, 1, v10
	v_lshlrev_b32_e32 v118, 1, v12
	v_lshlrev_b32_e32 v120, 1, v14
	v_add_u32_e32 v242, v7, v23
	v_add_u32_e32 v243, v11, v25
	v_lshlrev_b32_e32 v122, 2, v4
	v_lshlrev_b32_e32 v124, 2, v18
	v_lshlrev_b32_e32 v126, 2, v20
	v_lshlrev_b32_e32 v128, 2, v22
	v_lshlrev_b32_e32 v130, 2, v24
	v_lshlrev_b32_e32 v132, 2, v26
	v_lshlrev_b32_e32 v134, 2, v28
	v_lshlrev_b32_e32 v136, 2, v30
	v_lshlrev_b32_e32 v138, 2, v32
	v_lshlrev_b32_e32 v140, 2, v16
	v_lshlrev_b32_e32 v142, 2, v34
	v_lshlrev_b32_e32 v144, 2, v36
	v_lshlrev_b32_e32 v146, 2, v38
	v_add_u32_e32 v244, v13, v21
	v_add_u32_e32 v245, v15, v17
	v_add_u32_e32 v246, v19, v17
	v_readlane_b32 s31, v255, 40
	s_nop 4
	v_readlane_b32 s57, v253, 18
	s_branch .LBB0_266

; #define LAS __attribute__((address_space(3)))
; #define LAUNDER() int tp = TID0(); const int tid = tp, lane = tp & 63, wave = __builtin_amdgcn_readfirstlane(tp >> 6); (void)tid; (void)lane; (void)wave
; __global__ void __launch_bounds__(512) fwd_kernel(Args a) {
;     ...
;             if (EN_S1) { LAUNDER(); __syncthreads();
;                 for (int u = blockIdx.x; u < 256; u += G) ssd_part1_unit(u, PROJ, DT, H, WDT + l * 16384, a.in[11] + l * 8, a.in[8] + l * 5 * 768, a.in[9] + l * 768, a.in[10] + l * 8, STATES, TOT, lds, tid, wave, lane);
;                 __syncthreads(); }
;             if (EN_A) { LAUNDER(); LAS char* vt = (LAS char*)lds + wave * 16384;
;                 for (int u = blockIdx.x; u < 512; u += G) { mixerA1_unit(u, PROJ, YC, LPA, KMAX + l * 1024, vt, wave, lane); } }
;             if (EN_D) { LAUNDER(); LAS char* vt = (LAS char*)lds + wave * 16384;
;                 int hcur = -1; float rmax = 0.f;
;                 for (int u = blockIdx.x; u < 512; u += G) { const int hd = (u >> 4) & 3; if (hd != hcur) { rmax = d_stage_rpb(a.in[14] + l * 4 * 15 * 31, hd, vt, lane); hcur = hd; }
;                     mixerD2_unit(u, PROJ, YC, rmax, KMAX + l * 1024, vt, wave, lane); } }
.LBB0_356:
	s_cmp_eq_u32 s101, 5
	s_cbranch_scc0 .Lmx_a1_go
	s_mov_b32 s101, 0
	v_readlane_b32 s94, v255, 33
	v_readlane_b32 s96, v255, 19
	v_readlane_b32 s95, v255, 34
	v_readlane_b32 s97, v255, 20
	s_branch .LBB0_369

; #define LAS __attribute__((address_space(3)))
; #define LAUNDER() int tp = TID0(); const int tid = tp, lane = tp & 63, wave = __builtin_amdgcn_readfirstlane(tp >> 6); (void)tid; (void)lane; (void)wave
; #define SEAM(k) do { if (lo <= (k) && (k) + 1 < hi) { XcdBarrier b2_ = bar; asm volatile("" : "+s"(b2_.bar)); xcd_barrier(b2_); } } while (0)
; __global__ void __launch_bounds__(512) fwd_kernel(Args a) {
;     ...
;         if (IN(pb + 2)) {
;             if (EN_B) { LAUNDER(); LAS char* vt = (LAS char*)lds + wave * 16384;
;                 (void)vt; for (int u = blockIdx.x; u < 256; u += G) { mixerB2_unit(u, l, PROJ, YC, a.in[6] + l * 128, a.in[7] + l * 64, KMAX + l * 1024, (LAS char*)lds, tid, wave, lane); } __syncthreads(); }
;             if (EN_S1) { LAUNDER(); __syncthreads();
;                 for (int u = blockIdx.x; u < 256; u += G) ssd_part1_unit(u, PROJ, DT, H, WDT + l * 16384, a.in[11] + l * 8, a.in[8] + l * 5 * 768, a.in[9] + l * 768, a.in[10] + l * 8, STATES, TOT, lds, tid, wave, lane);
;                 __syncthreads(); }
;             if (EN_A) { LAUNDER(); LAS char* vt = (LAS char*)lds + wave * 16384;
;                 for (int u = blockIdx.x; u < 512; u += G) { mixerA1_unit(u, PROJ, YC, LPA, KMAX + l * 1024, vt, wave, lane); } }
;             if (EN_D) { LAUNDER(); LAS char* vt = (LAS char*)lds + wave * 16384;
;                 int hcur = -1; float rmax = 0.f;
;                 for (int u = blockIdx.x; u < 512; u += G) { const int hd = (u >> 4) & 3; if (hd != hcur) { rmax = d_stage_rpb(a.in[14] + l * 4 * 15 * 31, hd, vt, lane); hcur = hd; }
;                     mixerD2_unit(u, PROJ, YC, rmax, KMAX + l * 1024, vt, wave, lane); } }
;         }
;         SEAM(pb + 2);
.Lmx_e3b:
	s_cmp_eq_u32 s101, 3
	s_cbranch_scc0 .Lmx_done
	s_mov_b32 s101, 4
	s_branch .Lmx_b
